# grid barrier: member workgroups poll the top-level generation word directly (single-hop release); per-XCD generation bump by the leaders removed
# baseline (speedup 1.0000x reference)
; __device__ __forceinline__ unsigned xb_ld(unsigned* p)              { return __hip_atomic_load(p, __ATOMIC_RELAXED, __HIP_MEMORY_SCOPE_AGENT); }
; #define XB_SPIN(cond, bar) do { unsigned _sp = 0; while (cond) { __builtin_amdgcn_s_sleep(1); \
;     if ((++_sp & 255u) == 0u) { if (xb_ld(&(bar)[XB_TMO])) break; if (_sp > XB_SPIN_CAP) { atomicAdd(&(bar)[XB_TMO], 1u); break; } } } } while (0)
; __device__ __forceinline__ void xcd_barrier(const XcdBarrier& b, int tid_) {
;     ...
;         } else {
;             XB_SPIN(xb_ld(&bar[XB_XGEN(b.x)]) == gen, bar);
;             __builtin_amdgcn_fence(__ATOMIC_ACQUIRE, "agent");
.LBB0_980:
	s_or_b64 exec, exec, s[4:5]
	v_cvt_f32_u32_e32 v5, v3
	s_waitcnt vmcnt(0)
	buffer_inv sc1
	v_readfirstlane_b32 s2, v4
	v_sub_u32_e32 v4, 0, v3
	v_rcp_iflag_f32_e32 v5, v5
	v_add_u32_e32 v6, s2, v0
	v_mul_f32_e32 v5, 0x4f7ffffe, v5
	v_cvt_u32_f32_e32 v5, v5
	v_mul_lo_u32 v0, v4, v5
	v_mul_hi_u32 v0, v5, v0
	v_add_u32_e32 v0, v5, v0
	v_mul_hi_u32 v0, v6, v0
	v_mul_lo_u32 v4, v0, v3
	v_sub_u32_e32 v4, v6, v4
	v_add_u32_e32 v5, 1, v0
	v_cmp_ge_u32_e32 vcc, v4, v3
	s_nop 1
	v_cndmask_b32_e32 v0, v0, v5, vcc
	v_sub_u32_e32 v5, v4, v3
	v_cndmask_b32_e32 v4, v4, v5, vcc
	v_add_u32_e32 v5, 1, v0
	v_cmp_ge_u32_e32 vcc, v4, v3
	v_add_u32_e32 v4, 1, v6
	s_nop 0
	v_cndmask_b32_e32 v0, v0, v5, vcc
	v_mul_lo_u32 v5, v3, v0
	v_add_u32_e32 v3, v5, v3
	v_cmp_ne_u32_e32 vcc, v4, v3
	s_and_saveexec_b64 s[4:5], vcc
	s_xor_b64 s[4:5], exec, s[4:5]
	s_cbranch_execz .LBB0_994
	v_readlane_b32 s6, v254, 6
	v_readlane_b32 s7, v254, 7
	s_waitcnt lgkmcnt(0)
	s_nop 3
	global_load_dword v2, v1, s[6:7] sc1
	s_waitcnt vmcnt(0)
	v_cmp_eq_u32_e32 vcc, v2, v0
	s_and_saveexec_b64 s[6:7], vcc
	s_cbranch_execz .LBB0_993
	s_mov_b32 s2, 1
	s_mov_b64 s[8:9], 0
	s_branch .LBB0_984

; __device__ __forceinline__ unsigned xb_add(unsigned* p, unsigned v) { return __hip_atomic_fetch_add(p, v, __ATOMIC_RELAXED, __HIP_MEMORY_SCOPE_AGENT); }
; __device__ __forceinline__ void xcd_barrier(const XcdBarrier& b, int tid_) {
;     ...
;             xb_add(&bar[XB_XGEN(b.x)], 1u);
;             asm volatile("s_waitcnt vmcnt(0)" ::: "memory");
.LBB0_1011:
	s_or_b64 exec, exec, s[4:5]
	s_mov_b64 s[4:5], exec
	v_mbcnt_lo_u32_b32 v0, s4, 0
	v_mbcnt_hi_u32_b32 v0, s5, v0
	v_cmp_eq_u32_e32 vcc, 0, v0
	s_waitcnt vmcnt(0)
	s_and_saveexec_b64 s[6:7], vcc
	s_cbranch_execz .Ltramp_b16
	s_bcnt1_i32_b64 s2, s[4:5]
	v_readlane_b32 s4, v254, 2
	v_mov_b32_e32 v0, s2
	v_readlane_b32 s5, v254, 3
	s_nop 4
	s_branch .Ltramp_b16
